# attention: one static s_setprio 1 for waves 4-7 at pass entry (reset to 0 at phase exit)
# baseline (speedup 1.0000x reference)
; #define LAS __attribute__((address_space(3)))
; DI unsigned xb_ld(unsigned* p)              { return __hip_atomic_load(p, __ATOMIC_RELAXED, __HIP_MEMORY_SCOPE_AGENT); }
; DI unsigned xb_add(unsigned* p, unsigned v) { return __hip_atomic_fetch_add(p, v, __ATOMIC_RELAXED, __HIP_MEMORY_SCOPE_AGENT); }
; DI void xcd_barrier_complete(unsigned* bar, unsigned x, unsigned& nloc, unsigned& nx) {
;     const unsigned G = gridDim.x;
;     unsigned sum, cnt, mine, sp = 0u;
;     for (;;) {
;         sum = 0u; cnt = 0u; mine = 0u;
; #pragma unroll
;         for (unsigned j = 0; j < 16; ++j) { const unsigned c = xb_ld(&bar[XB_XCNT(j)]); sum += c; cnt += (c > 0u) ? 1u : 0u; mine = (j == x) ? c : mine; }
; DI void xcd_barrier(unsigned* bar, const unsigned x, volatile LAS unsigned* st) {
;     asm volatile("s_waitcnt vmcnt(0)" ::: "memory");
;     __syncthreads();
;     if (threadIdx.x == 0) {
;         __builtin_amdgcn_s_waitcnt(0);
;         unsigned nloc = st[0], nx = st[1];
;         if (nloc == 0u) { xcd_barrier_complete(bar, x, nloc, nx); st[0] = nloc; st[1] = nx; }
;         const unsigned old = xb_add(&bar[XB_XSUB(x)], 1u);
.LBB0_1025:
	s_setprio 0
	s_mov_b64 s[6:7], s[0:1]
	s_waitcnt vmcnt(63) expcnt(7) lgkmcnt(15)
	s_barrier
	s_getreg_b32 s2, hwreg(HW_REG_XCC_ID, 0, 4)
	s_waitcnt vmcnt(0)
	s_barrier
	s_mov_b64 s[4:5], exec
	v_readlane_b32 s8, v255, 1
	v_readlane_b32 s9, v255, 2
	s_and_b64 s[8:9], s[4:5], s[8:9]
	s_xor_b64 s[4:5], s[8:9], s[4:5]
	s_mov_b32 s66, 0x3a800000
	s_mov_b64 exec, s[8:9]
	s_cbranch_execz .LBB0_1122
	v_readlane_b32 s8, v255, 53
	s_load_dwordx2 s[6:7], s[6:7], 0x110
	s_waitcnt vmcnt(0) expcnt(0) lgkmcnt(0)
	v_mov_b32_e32 v0, s8
	ds_read_b32 v2, v0
	v_readlane_b32 s8, v255, 54
	s_and_b32 s2, s2, 15
	s_waitcnt lgkmcnt(0)
	v_cmp_ne_u32_e32 vcc, 0, v2
	v_mov_b32_e32 v0, s8
	ds_read_b32 v0, v0
	s_cbranch_vccnz .LBB0_1085
	s_add_u32 s8, s6, 0x1200
	s_addc_u32 s9, s7, 0
	s_add_u32 s10, s6, 0x1400
	s_addc_u32 s11, s7, 0
	s_add_u32 s12, s6, 0x1500
	s_addc_u32 s13, s7, 0
	s_add_u32 s14, s6, 0x1600
	s_addc_u32 s15, s7, 0
	s_add_u32 s16, s6, 0x1700
	s_addc_u32 s17, s7, 0
	s_add_u32 s18, s6, 0x1800
	s_addc_u32 s19, s7, 0
	s_add_u32 s20, s6, 0x1900
	s_addc_u32 s21, s7, 0
	s_add_u32 s22, s6, 0x1a00
	s_addc_u32 s23, s7, 0
	s_add_u32 s24, s6, 0x1b00
	s_addc_u32 s25, s7, 0
	s_add_u32 s26, s6, 0x1c00
	s_addc_u32 s27, s7, 0
	s_add_u32 s28, s6, 0x1d00
	s_addc_u32 s29, s7, 0
	s_add_u32 s34, s6, 0x1e00
	s_addc_u32 s35, s7, 0
	s_add_u32 s36, s6, 0x1f00
	s_addc_u32 s37, s7, 0
	s_add_u32 s40, s6, 0x2000
	s_addc_u32 s41, s7, 0
	s_add_u32 s42, s6, 0x2100
	s_addc_u32 s43, s7, 0
	s_add_u32 s44, s6, 0x2200
	s_addc_u32 s45, s7, 0
	s_add_u32 s46, s6, 0x2300
	s_addc_u32 s47, s7, 0
	s_mov_b32 s30, 1
	s_branch .LBB0_1073

; DI int v_st(int k, int c) { const int kk = (k & ~0xC) | ((k & 4) << 1) | ((k & 8) >> 1); return ((kk >> 3) * 4 + (c >> 5)) * 512 + ((kk & 7) * 32 + (c & 31)) * 2; }
; DI int v_rd_base(int lane) { return ((lane & 3) << 3) | (((lane >> 2) & 3) << 6) | (((lane >> 4) & 1) << 5) | (((lane >> 5) & 1) << 8); }
; #define SLOADA(k0) do { vsA0 = *reinterpret_cast<const bf16x8*>(&Vh[(size_t)((k0) + sr) * LDQ + sc]); vsA1 = *reinterpret_cast<const bf16x8*>(&Vh[(size_t)((k0) + 32 + sr) * LDQ + sc]); \
;     ksA = *reinterpret_cast<const bf16x8*>(&Kh[(size_t)((k0) + kr) * LDQ + kc]); } while (0)
; #define SWRITEA(b) do { *(bf16x8*)(V_lds + (b) * SHM_V + vst0) = vsA0; *(bf16x8*)(V_lds + (b) * SHM_V + vst1) = vsA1; *(bf16x8*)(K_lds + (b) * SHM_K + kst) = ksA; } while (0)
; DI void attn_pass(const bf16_t* __restrict__ Qb, const bf16_t* __restrict__ Kh, const bf16_t* __restrict__ Vh, int seq, char* lds, f32x16 (&o)[4], float& l_out) {
;     int tid_ = threadIdx.x; asm volatile("" : "+v"(tid_));
;     const int tid = tid_, wid = tid >> 6, lane = tid & 63, r32 = lane & 31, hi = lane >> 5;
;     char* V_lds = lds; char* K_lds = lds + 2 * SHM_V;
;     float* ws = (float*)(lds + 2 * SHM_V + 2 * SHM_K) + wid * 64; float* al_l = ws + 32;
;     float m_reg = -1e30f, l_reg = 0; bf16x8 qr[4]; f32x16 negm;
; #pragma unroll
;     for (int r = 0; r < 16; ++r) negm[r] = 0.f;
; #pragma unroll
;     for (int d = 0; d < 4; ++d)
; #pragma unroll
;         for (int r = 0; r < 16; ++r) o[d][r] = 0.f;
;     const bf16_t* Qw = Qb + (size_t)(wid * QBLK + r32) * LDQ + hi * 8;
; #pragma unroll
;     for (int d0 = 0; d0 < 4; ++d0) qr[d0] = *reinterpret_cast<const bf16x8*>(Qw + d0 * 16);
;     const int sr = tid >> 4, sc = (tid & 15) * 8, vst0 = v_st(sr, sc), vst1 = v_st(32 + sr, sc);
;     const int kr = tid >> 3, kc = (tid & 7) * 8, kst = KSWZ(kr, kc * 2);
;     const int vb0 = (int)(uintptr_t)V_lds + v_rd_base(lane);
;     bf16x8 vsA0, vsA1, ksA, vsB0, vsB1, ksB;
;     ...
;     f32x16 pA0, pA1, pB0, pB1; float alA, alB; bf16x8 pa0, pa1, pa2, pa3; const int NT = seq / KVBLK;
;     SLOADA(0); asm volatile("s_waitcnt vmcnt(0)" ::: "memory"); SWRITEA(0); __syncthreads();
;     qkt(pA0, pA1, K_lds, qr, negm, r32, hi); partialSM(pA0, pA1, m_reg, negm, alA);
.LBB0_1035:
	s_mov_b64 s[8:9], s[0:1]
	s_barrier
	v_readfirstlane_b32 s98, v199
	s_nop 3
	s_cmp_lt_u32 s98, 0x100
	s_cbranch_scc1 .Lattn_prio_done
	s_setprio 1
.Lattn_prio_done:
	s_load_dwordx2 s[8:9], s[8:9], 0x110
	v_mov_b32_e32 v28, v199
	v_mov_b32_e32 v25, v185
	v_mov_b32_e32 v21, v185
	s_waitcnt lgkmcnt(0)
	s_add_u32 s2, s8, s12
	s_addc_u32 s16, s9, s13
	s_mov_b64 s[8:9], s[0:1]
	s_lshl_b32 s30, s11, 1
	s_load_dwordx2 s[18:19], s[8:9], 0x110
	s_add_u32 s2, s2, s30
	s_addc_u32 s8, s16, 0
	s_lshl_b64 s[4:5], s[4:5], 1
	s_add_u32 s16, s2, s4
	s_addc_u32 s17, s8, s5
	s_waitcnt lgkmcnt(0)
	s_add_u32 s2, s18, s14
	s_addc_u32 s8, s19, s15
	s_add_u32 s2, s2, s30
	s_addc_u32 s24, s8, 0
	s_mov_b64 s[8:9], s[0:1]
	s_load_dwordx2 s[8:9], s[8:9], 0x110
	s_add_u32 s2, s2, s4
	s_addc_u32 s25, s24, s5
	s_add_u32 s24, s2, 0x13c00000
	s_addc_u32 s25, s25, 0
	s_waitcnt lgkmcnt(0)
	s_add_u32 s2, s8, s14
	s_addc_u32 s26, s9, s15
	s_add_u32 s2, s2, s30
	s_addc_u32 s27, s26, 0
	v_ashrrev_i32_e32 v12, 4, v28
	v_add_u32_e32 v14, 32, v12
	s_add_u32 s26, s2, 0x19c00000
	v_lshlrev_b32_e32 v36, 3, v28
	v_ashrrev_i32_e32 v13, 31, v12
	v_ashrrev_i32_e32 v15, 31, v14
	s_addc_u32 s27, s27, 0
	v_and_b32_e32 v0, 0x78, v36
	v_ashrrev_i32_e32 v30, 3, v28
	v_lshlrev_b64 v[16:17], 11, v[12:13]
	v_lshlrev_b64 v[2:3], 11, v[14:15]
	v_and_b32_e32 v1, 56, v36
	v_lshl_add_u64 v[22:23], s[26:27], 0, v[16:17]
	v_lshlrev_b32_e32 v24, 1, v0
	v_lshl_add_u64 v[2:3], s[26:27], 0, v[2:3]
	v_ashrrev_i32_e32 v31, 31, v30
	v_lshlrev_b32_e32 v20, 1, v1
	v_lshl_add_u64 v[0:1], v[22:23], 0, v[24:25]
	v_lshl_add_u64 v[4:5], v[2:3], 0, v[24:25]
	v_lshlrev_b64 v[18:19], 11, v[30:31]
	global_load_dwordx4 v[0:3], v[0:1], off
	s_nop 0
	global_load_dwordx4 v[4:7], v[4:5], off
	v_lshl_add_u64 v[26:27], s[24:25], 0, v[18:19]
	v_lshl_add_u64 v[8:9], v[26:27], 0, v[20:21]
	global_load_dwordx4 v[8:11], v[8:9], off
	v_ashrrev_i32_e32 v13, 1, v28
	s_movk_i32 s2, 0xffe0
	v_bfi_b32 v32, s2, v13, v28
	v_ashrrev_i32_e32 v33, 31, v32
	v_lshlrev_b64 v[32:33], 11, v[32:33]
	v_lshrrev_b32_e32 v13, 1, v28
	v_lshl_add_u64 v[32:33], s[16:17], 0, v[32:33]
	v_and_b32_e32 v184, 16, v13
	v_lshl_add_u64 v[32:33], v[32:33], 0, v[184:185]
	v_add_co_u32_e32 v34, vcc, s96, v32
	v_and_b32_e32 v21, 0xfffff0, v12
	s_nop 0
	v_addc_co_u32_e32 v35, vcc, 0, v33, vcc
	global_load_dwordx4 v[148:151], v[34:35], off
	v_lshl_add_u64 v[32:33], v[32:33], 0, s[86:87]
	global_load_dwordx4 v[144:147], v[32:33], off offset:32
	global_load_dwordx4 v[152:155], v[32:33], off offset:64
	global_load_dwordx4 v[156:159], v[32:33], off offset:96
	v_lshlrev_b32_e32 v25, 1, v12
	v_and_or_b32 v21, v25, 8, v21
	v_and_b32_e32 v25, 0xfffff0, v14
	v_lshlrev_b32_e32 v14, 1, v14
	v_and_b32_e32 v15, 0x70, v28
	v_lshrrev_b32_e32 v31, 1, v12
	v_bfe_u32 v34, v36, 5, 2
	v_and_b32_e32 v12, 3, v12
	v_lshlrev_b32_e32 v30, 7, v30
	v_lshrrev_b32_e32 v21, 1, v21
	v_and_or_b32 v14, v14, 8, v25
	v_lshlrev_b32_e32 v13, 4, v28
	v_and_or_b32 v12, v31, 4, v12
	v_bitop3_b32 v15, v20, v30, v15 bitop3:0xde
	v_or_b32_e32 v21, v21, v34
	v_lshrrev_b32_e32 v14, 1, v14
	v_and_b32_e32 v13, 48, v13
	v_lshlrev_b32_e32 v12, 6, v12
	v_add_u32_e32 v213, 0, v15
	v_lshlrev_b32_e32 v15, 9, v21
	v_or_b32_e32 v14, v14, v34
	v_and_b32_e32 v29, 31, v28
	v_or3_b32 v15, v15, v12, v13
	v_lshlrev_b32_e32 v14, 9, v14
	v_or3_b32 v12, v14, v12, v13
	v_add_u32_e32 v214, 0, v15
	v_lshlrev_b32_e32 v21, 7, v29
	v_and_b32_e32 v25, 0x70, v36
	v_add_u32_e32 v215, 0, v12
	s_waitcnt vmcnt(0)
	s_mov_b32 s24, 0
	s_cmp_eq_u64 exec, 0
	s_waitcnt vmcnt(6)
	ds_write_b128 v214, v[0:3]
	s_waitcnt vmcnt(5)
	ds_write_b128 v215, v[4:7]
	s_waitcnt vmcnt(4)
	ds_write_b128 v213, v[8:11] offset:32768
	v_bitop3_b32 v0, v184, v21, v25 bitop3:0xde
	v_add_u32_e32 v217, 0, v0
	s_waitcnt lgkmcnt(0)
	s_barrier
	ds_read_b128 v[0:3], v217 offset:32768
	ds_read_b128 v[30:33], v217 offset:36864
	s_waitcnt vmcnt(3) lgkmcnt(0)
	v_mfma_f32_32x32x16_bf16 v[96:111], v[30:33], v[148:151], 0
	v_or_b32_e32 v30, 32, v184
	v_bitop3_b32 v30, v30, v21, v25 bitop3:0xde
	v_add_u32_e32 v218, 0, v30
	ds_read_b128 v[30:33], v218 offset:32768
	v_mfma_f32_32x32x16_bf16 v[0:15], v[0:3], v[148:151], 0
	s_waitcnt vmcnt(2) lgkmcnt(0)
	v_mfma_f32_32x32x16_bf16 v[0:15], v[30:33], v[144:147], v[0:15]
	ds_read_b128 v[30:33], v218 offset:36864
	s_waitcnt lgkmcnt(0)
	v_mfma_f32_32x32x16_bf16 v[96:111], v[30:33], v[144:147], v[96:111]
	v_or_b32_e32 v30, 64, v184
	v_bitop3_b32 v30, v30, v21, v25 bitop3:0xde
	v_add_u32_e32 v219, 0, v30
	ds_read_b128 v[30:33], v219 offset:32768
	s_waitcnt vmcnt(1) lgkmcnt(0)
	v_mfma_f32_32x32x16_bf16 v[0:15], v[30:33], v[152:155], v[0:15]
	ds_read_b128 v[30:33], v219 offset:36864
	s_waitcnt lgkmcnt(0)
	v_mfma_f32_32x32x16_bf16 v[96:111], v[30:33], v[152:155], v[96:111]
	v_or_b32_e32 v30, 0x60, v184
	v_bitop3_b32 v21, v30, v21, v25 bitop3:0xde
	v_add_u32_e32 v216, 0, v21
	ds_read_b128 v[30:33], v216 offset:32768
	s_waitcnt vmcnt(0) lgkmcnt(0)
	v_mfma_f32_32x32x16_bf16 v[0:15], v[30:33], v[156:159], v[0:15]
	ds_read_b128 v[30:33], v216 offset:36864
	s_nop 10
	v_max_f32_e32 v21, v1, v1
	v_max_f32_e32 v25, v0, v0
	s_waitcnt lgkmcnt(0)
	v_mfma_f32_32x32x16_bf16 v[96:111], v[30:33], v[156:159], v[96:111]
	v_max_f32_e32 v21, v25, v21
	v_max3_f32 v21, v21, v2, v3
	v_max3_f32 v21, v21, v4, v5
	v_max3_f32 v21, v21, v6, v7
	v_max3_f32 v21, v21, v8, v9
	v_max3_f32 v21, v21, v10, v11
	v_max3_f32 v21, v21, v12, v13
	v_max3_f32 v21, v21, v14, v15
	s_nop 3
	v_max3_f32 v21, v21, v96, v97
	v_max3_f32 v21, v21, v98, v99
	v_max3_f32 v21, v21, v100, v101
	v_max3_f32 v21, v21, v102, v103
	v_max3_f32 v21, v21, v104, v105
	v_max3_f32 v21, v21, v106, v107
	v_max3_f32 v21, v21, v108, v109
	v_max3_f32 v21, v21, v110, v111
	v_mov_b32_e32 v25, v21
	s_nop 1
	v_permlane32_swap_b32_e32 v21, v25
	s_cbranch_scc0 .LBB0_1070
	v_mov_b32_e32 v64, 0
	s_mov_b32 s24, 1.0
	v_mov_b32_e32 v200, 0xf149f2ca
